# v15 + EpiMix sigmoid gate blocks packed/batched + P0: double-adaLN waves skip weight copy
# speedup vs baseline: 1.0006x; 1.0006x over previous
; #define LAS __attribute__((address_space(3)))
; __device__ __forceinline__ void p_convert(const Frame& F, const WSrc& S, bf16* Wb, unsigned mask) {
;     LAS float* scr = (LAS float*)(F.lds + F.wave * 16384);
;     const int gw = F.vcu * NWAVES + F.wave, NGW = F.G * NWAVES;
;     constexpr int IT_GU = (DM / 64) * (FFN / 32), IT_D = (FFN / 64) * (DM / 32), IT_IN = (DM / 64) * (3584 / 32), IT_MG = (DM / 64) * (6144 / 32), IT_B5 = (512 / 64) * (DM / 32), IT_B10 = (1024 / 64) * (DM / 32), IT_O = (DM / 64) * (DM / 32);
;     ...
;     const int NIT = (int)(ON(0) + ON(1) + ON(9) + ON(10)) * IT_GU + (int)(ON(2) + ON(11)) * IT_D + (int)ON(3) * IT_IN + (int)ON(4) * IT_MG + (int)(ON(5) + ON(7)) * IT_B5 + (int)ON(6) * IT_B10 + (int)ON(8) * IT_O;
;     ...
;     if (gw >= NIT) return;
;     const float* W; int ldw, K, drow0, k0, n0; bf16* WT; f32x4 v[8];
;     cvt_decode(gw, S, Wb, mask, W, ldw, K, WT, drow0, k0, n0); cvt_load(v, W, ldw, k0, n0, F.lane);
; __global__ void __launch_bounds__(NTHR, 2) mk_fwd(Args args) {
;     ...
;         __syncthreads();
;         { WSrc S{IN(7), IN(8), IN(9), IN(11), IN(18), IN(15), IN(16), IN(17), IN(20), IN(22), IN(23), IN(24)}; p_convert(P, S, P_WB, 0x003u); }
.LBB0_20:
	s_barrier
	s_cmpk_lg_u32 s15, 0x800
	s_cbranch_scc1 .Lp0_orig
	s_cmpk_lt_i32 s14, 0x100
	s_cbranch_scc1 .LBB0_33
	s_addk_i32 s14, 0xff00
	s_addk_i32 s15, 0xff00
.Lp0_orig:
	s_cmpk_gt_i32 s14, 0x2bff
	s_cbranch_scc1 .LBB0_33
	s_load_dwordx4 s[4:7], s[0:1], 0x38
	s_cmpk_gt_i32 s14, 0x15ff
	s_cbranch_scc0 .LBB0_23
	s_add_i32 s0, s14, 0xea00
	s_and_b32 s1, s0, 0xffff
	s_mul_i32 s1, s1, 0xba2f
	s_lshr_b32 s1, s1, 23
	s_mul_i32 s2, s1, 0xb0
	s_sub_i32 s0, s0, s2
	s_and_b32 s0, s0, 0xffff
	s_lshl_b32 s2, s0, 5
	s_lshl_b32 s0, s0, 6
	s_lshl_b32 s24, s1, 6
	s_and_b32 s0, s0, 0x3f00
	s_and_b32 s1, s2, 0x60
	s_or_b32 s0, s1, s0
	s_or_b32 s17, s0, 0x80
	s_waitcnt lgkmcnt(0)
	s_mov_b64 s[8:9], s[6:7]
	s_cbranch_execz .LBB0_24
	s_branch .LBB0_25

;     __device__ __forceinline__ void operator()(const f32x4 (&acc)[2][2][4][2], const Unit& u, int wr, int wc, int fr_, int fq) const {
;     ...
;         const int pn = u.pn; bf16_t* O; int ld, colt; size_t rowt = (size_t)u.pm * BM; const bool gate = pn >= 14;
;         if (pn < 4) { O = Q; ld = 1024; colt = pn * BM; }
;         else if (pn < 6) { O = (pn == 4) ? K : V; ld = 256; colt = 0; rowt = (u.pm < NLAT_TILES) ? (size_t)(u.pm >> 3) * 2304 + 256 + (size_t)(u.pm & 7) * BM : (size_t)(u.pm - NLAT_TILES) * 2304; }
;         else if (pn < 14) { O = R; ld = 2048; colt = (pn - 6) * BM; }
;         else { O = G; ld = 6144; colt = (pn - 14) * BM; }
.LBB0_597:
	v_mov_b32_e32 v188, 0xbfb8aa3b
	v_mov_b32_e32 v189, 0xbfb8aa3b
	v_mov_b32_e32 v190, 1.0
	v_mov_b32_e32 v191, 1.0
	s_ashr_i32 s29, s28, 31
	s_lshl_b64 s[40:41], s[28:29], 8
	v_mov_b32_e32 v162, v168
	s_cmp_gt_i32 s8, 3
	s_mov_b64 s[60:61], -1
	s_cbranch_scc0 .LBB0_611
	s_cmp_gt_u32 s8, 5
	s_mov_b64 s[36:37], -1
	s_cbranch_scc0 .LBB0_604
	s_lshl_b32 s9, s8, 8
	s_cmp_gt_u32 s8, 13
	s_mov_b64 s[0:1], -1
	s_cbranch_scc0 .LBB0_601
	s_add_i32 s34, s9, 0xfffff200
	s_mov_b64 s[0:1], 0

; __device__ __forceinline__ float fast_sigmoid(float x) { return __builtin_amdgcn_rcpf(1.0f + __builtin_amdgcn_exp2f(-1.4426950408889634f * x)); }
; __device__ __forceinline__ u32x4 pack8(const f32x4 v0, const f32x4 v1) { u32x4 w; w.x = cvt_pk_bf16(v0[0], v0[1]); w.y = cvt_pk_bf16(v0[2], v0[3]); w.z = cvt_pk_bf16(v1[0], v1[1]); w.w = cvt_pk_bf16(v1[2], v1[3]); return w; }
;     __device__ __forceinline__ void operator()(const f32x4 (&acc)[2][2][4][2], const Unit& u, int wr, int wc, int fr_, int fq) const {
;     ...
;         for (int bj = 0; bj < 2; ++bj)
; #pragma unroll
;             for (int n = 0; n < 2; ++n) bv[bj][n] = *(const f32x4*)(bmg + (gate ? colt : 0) + cl + bj * HALF + 4 * n) * (gate ? 1.0f : 0.0f);
;         bf16_t* ob = O + (rowt + wr * 64 + fr) * ld + colt + cl;
; #pragma unroll
;         for (int ai = 0; ai < 2; ++ai)
; #pragma unroll
;             for (int m = 0; m < 4; ++m)
; #pragma unroll
;                 for (int bj = 0; bj < 2; ++bj) { f32x4 v0 = acc[ai][bj][m][0], v1 = acc[ai][bj][m][1];
;                     v0 += bv[bj][0]; v1 += bv[bj][1];
;                     if (gate) {
; #pragma unroll
;                         for (int j = 0; j < 4; ++j) { v0[j] = fast_sigmoid(v0[j]); v1[j] = fast_sigmoid(v1[j]); } }
;                     *(u32x4*)(ob + (size_t)(ai * HALF + m * 16) * ld + bj * HALF) = pack8(v0, v1); }
.LBB0_613:
	s_cmp_gt_i32 s8, 13
	s_cselect_b64 s[28:29], -1, 0
	s_and_b64 s[40:41], s[28:29], exec
	s_cselect_b32 s40, s34, 0
	s_ashr_i32 s41, s40, 31
	v_lshl_add_u64 v[134:135], s[40:41], 2, v[154:155]
	global_load_dwordx4 v[142:145], v[134:135], off
	global_load_dwordx4 v[138:141], v[134:135], off offset:16
	global_load_dwordx4 v[130:133], v[134:135], off offset:528
	s_nop 0
	global_load_dwordx4 v[134:137], v[134:135], off offset:512
	v_cndmask_b32_e64 v160, 0, 1.0, s[28:29]
	s_cmp_lt_i32 s8, 14
	s_waitcnt vmcnt(0)
	v_pk_fma_f32 v[128:129], v[160:161], v[144:145], v[128:129] op_sel_hi:[0,1,1]
	v_pk_fma_f32 v[164:165], v[160:161], v[142:143], v[126:127] op_sel_hi:[0,1,1]
	v_pk_fma_f32 v[126:127], v[160:161], v[140:141], v[124:125] op_sel_hi:[0,1,1]
	v_pk_fma_f32 v[166:167], v[160:161], v[138:139], v[122:123] op_sel_hi:[0,1,1]
	s_cbranch_scc1 .LBB0_615
	v_pk_mul_f32 v[192:193], v[126:127], v[188:189]
	v_pk_mul_f32 v[224:225], v[128:129], v[188:189]
	v_pk_mul_f32 v[226:227], v[164:165], v[188:189]
	v_pk_mul_f32 v[228:229], v[166:167], v[188:189]
	v_exp_f32_e32 v192, v192
	v_exp_f32_e32 v193, v193
	v_exp_f32_e32 v224, v224
	v_exp_f32_e32 v225, v225
	v_exp_f32_e32 v226, v226
	v_exp_f32_e32 v227, v227
	v_exp_f32_e32 v228, v228
	v_exp_f32_e32 v229, v229
	v_pk_add_f32 v[192:193], v[192:193], v[190:191]
	v_pk_add_f32 v[224:225], v[224:225], v[190:191]
	v_pk_add_f32 v[226:227], v[226:227], v[190:191]
	v_pk_add_f32 v[228:229], v[228:229], v[190:191]
	v_rcp_f32_e32 v126, v192
	v_rcp_f32_e32 v127, v193
	v_rcp_f32_e32 v128, v224
	v_rcp_f32_e32 v129, v225
	v_rcp_f32_e32 v164, v226
	v_rcp_f32_e32 v165, v227
	v_rcp_f32_e32 v166, v228
	v_rcp_f32_e32 v167, v229
.LBB0_615:
	s_add_u32 s8, s36, s89
	v_ashrrev_i32_e32 v163, 31, v162
	s_addc_u32 s9, s37, s92
	v_lshl_add_u64 v[124:125], s[8:9], 0, v[162:163]
	v_mul_lo_u32 v162, v125, s30
	v_mul_lo_u32 v163, v124, s31
	v_mad_u64_u32 v[124:125], s[8:9], v124, s30, 0
	v_add3_u32 v125, v125, v163, v162
	v_lshl_add_u64 v[124:125], v[124:125], 1, s[0:1]
	s_ashr_i32 s35, s34, 31
	v_mov_b32_e32 v122, v160
	v_mov_b32_e32 v123, v160
	v_lshl_add_u64 v[124:125], s[34:35], 1, v[124:125]
	v_mov_b32_e32 v161, v160
	v_lshl_add_u64 v[124:125], v[124:125], 0, v[186:187]
	v_cvt_pk_bf16_f32 v162, v164, v165
	v_cvt_pk_bf16_f32 v163, v128, v129
	v_cvt_pk_bf16_f32 v164, v166, v167
	v_cvt_pk_bf16_f32 v165, v126, v127
	v_pk_fma_f32 v[128:129], v[122:123], v[132:133], v[116:117]
	v_cndmask_b32_e64 v116, 0, 1, s[28:29]
	global_store_dwordx4 v[124:125], v[162:165], off
	v_pk_fma_f32 v[126:127], v[122:123], v[136:137], v[120:121]
	v_cmp_ne_u32_e64 s[8:9], 1, v116
	v_pk_fma_f32 v[162:163], v[160:161], v[134:135], v[118:119]
	s_andn2_b64 vcc, exec, s[28:29]
	v_pk_fma_f32 v[164:165], v[160:161], v[130:131], v[114:115]
	s_cbranch_vccnz .LBB0_617
	v_pk_mul_f32 v[192:193], v[126:127], v[188:189]
	v_pk_mul_f32 v[224:225], v[128:129], v[188:189]
	v_pk_mul_f32 v[226:227], v[162:163], v[188:189]
	v_pk_mul_f32 v[228:229], v[164:165], v[188:189]
	v_exp_f32_e32 v192, v192
	v_exp_f32_e32 v193, v193
	v_exp_f32_e32 v224, v224
	v_exp_f32_e32 v225, v225
	v_exp_f32_e32 v226, v226
	v_exp_f32_e32 v227, v227
	v_exp_f32_e32 v228, v228
	v_exp_f32_e32 v229, v229
	v_pk_add_f32 v[192:193], v[192:193], v[190:191]
	v_pk_add_f32 v[224:225], v[224:225], v[190:191]
	v_pk_add_f32 v[226:227], v[226:227], v[190:191]
	v_pk_add_f32 v[228:229], v[228:229], v[190:191]
	v_rcp_f32_e32 v126, v192
	v_rcp_f32_e32 v127, v193
	v_rcp_f32_e32 v128, v224
	v_rcp_f32_e32 v129, v225
	v_rcp_f32_e32 v162, v226
	v_rcp_f32_e32 v163, v227
	v_rcp_f32_e32 v164, v228
	v_rcp_f32_e32 v165, v229
.LBB0_617:
	v_pk_mul_f32 v[118:119], v[160:161], v[144:145] op_sel_hi:[0,1]
	v_pk_mul_f32 v[120:121], v[160:161], v[142:143] op_sel_hi:[0,1]
	v_pk_mul_f32 v[116:117], v[160:161], v[140:141] op_sel_hi:[0,1]
	v_pk_mul_f32 v[114:115], v[160:161], v[138:139] op_sel_hi:[0,1]
	v_cvt_pk_bf16_f32 v138, v162, v163
	v_cvt_pk_bf16_f32 v139, v126, v127
	v_cvt_pk_bf16_f32 v140, v164, v165
	v_cvt_pk_bf16_f32 v141, v128, v129
	global_store_dwordx4 v[124:125], v[138:141], off offset:256
	v_pk_add_f32 v[126:127], v[112:113], v[118:119]
	v_pk_add_f32 v[128:129], v[110:111], v[120:121]
	v_pk_add_f32 v[138:139], v[108:109], v[116:117]
	s_and_b64 vcc, exec, s[8:9]
	v_pk_add_f32 v[140:141], v[106:107], v[114:115]
	s_cbranch_vccnz .LBB0_619
	v_pk_mul_f32 v[192:193], v[126:127], v[188:189]
	v_pk_mul_f32 v[224:225], v[128:129], v[188:189]
	v_pk_mul_f32 v[226:227], v[138:139], v[188:189]
	v_pk_mul_f32 v[228:229], v[140:141], v[188:189]
	v_exp_f32_e32 v192, v192
	v_exp_f32_e32 v193, v193
	v_exp_f32_e32 v224, v224
	v_exp_f32_e32 v225, v225
	v_exp_f32_e32 v226, v226
	v_exp_f32_e32 v227, v227
	v_exp_f32_e32 v228, v228
	v_exp_f32_e32 v229, v229
	v_pk_add_f32 v[192:193], v[192:193], v[190:191]
	v_pk_add_f32 v[224:225], v[224:225], v[190:191]
	v_pk_add_f32 v[226:227], v[226:227], v[190:191]
	v_pk_add_f32 v[228:229], v[228:229], v[190:191]
	v_rcp_f32_e32 v126, v192
	v_rcp_f32_e32 v127, v193
	v_rcp_f32_e32 v128, v224
	v_rcp_f32_e32 v129, v225
	v_rcp_f32_e32 v138, v226
	v_rcp_f32_e32 v139, v227
	v_rcp_f32_e32 v140, v228
	v_rcp_f32_e32 v141, v229
; __device__ __forceinline__ float fast_sigmoid(float x) { return __builtin_amdgcn_rcpf(1.0f + __builtin_amdgcn_exp2f(-1.4426950408889634f * x)); }
; __device__ __forceinline__ u32x4 pack8(const f32x4 v0, const f32x4 v1) { u32x4 w; w.x = cvt_pk_bf16(v0[0], v0[1]); w.y = cvt_pk_bf16(v0[2], v0[3]); w.z = cvt_pk_bf16(v1[0], v1[1]); w.w = cvt_pk_bf16(v1[2], v1[3]); return w; }
;     __device__ __forceinline__ void operator()(const f32x4 (&acc)[2][2][4][2], const Unit& u, int wr, int wc, int fr_, int fq) const {
;     ...
;         for (int ai = 0; ai < 2; ++ai)
; #pragma unroll
;             for (int m = 0; m < 4; ++m)
; #pragma unroll
;                 for (int bj = 0; bj < 2; ++bj) { f32x4 v0 = acc[ai][bj][m][0], v1 = acc[ai][bj][m][1];
;                     v0 += bv[bj][0]; v1 += bv[bj][1];
;                     if (gate) {
; #pragma unroll
;                         for (int j = 0; j < 4; ++j) { v0[j] = fast_sigmoid(v0[j]); v1[j] = fast_sigmoid(v1[j]); } }
;                     *(u32x4*)(ob + (size_t)(ai * HALF + m * 16) * ld + bj * HALF) = pack8(v0, v1); }
.LBB0_619:
	v_pk_mul_f32 v[110:111], v[122:123], v[136:137]
	v_pk_mul_f32 v[112:113], v[160:161], v[134:135]
	v_pk_mul_f32 v[108:109], v[122:123], v[132:133]
	v_pk_mul_f32 v[106:107], v[160:161], v[130:131]
	s_lshl_b64 s[0:1], s[30:31], 5
	v_lshl_add_u64 v[122:123], v[124:125], 0, s[0:1]
	v_pk_add_f32 v[104:105], v[104:105], v[110:111]
	v_pk_add_f32 v[102:103], v[102:103], v[112:113]
	v_pk_add_f32 v[100:101], v[100:101], v[108:109]
	s_and_b64 vcc, exec, s[8:9]
	v_pk_add_f32 v[98:99], v[98:99], v[106:107]
	v_cvt_pk_bf16_f32 v124, v128, v129
	v_cvt_pk_bf16_f32 v125, v126, v127
	v_cvt_pk_bf16_f32 v126, v140, v141
	v_cvt_pk_bf16_f32 v127, v138, v139
	global_store_dwordx4 v[122:123], v[124:127], off
	s_cbranch_vccnz .LBB0_621
	v_pk_mul_f32 v[192:193], v[98:99], v[188:189]
	v_pk_mul_f32 v[224:225], v[100:101], v[188:189]
	v_pk_mul_f32 v[226:227], v[102:103], v[188:189]
	v_pk_mul_f32 v[228:229], v[104:105], v[188:189]
	v_exp_f32_e32 v192, v192
	v_exp_f32_e32 v193, v193
	v_exp_f32_e32 v224, v224
	v_exp_f32_e32 v225, v225
	v_exp_f32_e32 v226, v226
	v_exp_f32_e32 v227, v227
	v_exp_f32_e32 v228, v228
	v_exp_f32_e32 v229, v229
	v_pk_add_f32 v[192:193], v[192:193], v[190:191]
	v_pk_add_f32 v[224:225], v[224:225], v[190:191]
	v_pk_add_f32 v[226:227], v[226:227], v[190:191]
	v_pk_add_f32 v[228:229], v[228:229], v[190:191]
	v_rcp_f32_e32 v98, v192
	v_rcp_f32_e32 v99, v193
	v_rcp_f32_e32 v100, v224
	v_rcp_f32_e32 v101, v225
	v_rcp_f32_e32 v102, v226
	v_rcp_f32_e32 v103, v227
	v_rcp_f32_e32 v104, v228
	v_rcp_f32_e32 v105, v229
.LBB0_621:
	v_cvt_pk_bf16_f32 v102, v102, v103
	v_cvt_pk_bf16_f32 v103, v104, v105
	v_cvt_pk_bf16_f32 v104, v98, v99
	v_pk_add_f32 v[96:97], v[96:97], v[118:119]
	v_pk_add_f32 v[94:95], v[94:95], v[120:121]
	v_pk_add_f32 v[92:93], v[92:93], v[116:117]
	s_and_b64 vcc, exec, s[8:9]
	v_pk_add_f32 v[98:99], v[90:91], v[114:115]
	v_cvt_pk_bf16_f32 v105, v100, v101
	global_store_dwordx4 v[122:123], v[102:105], off offset:256
	s_cbranch_vccnz .LBB0_623
	v_pk_mul_f32 v[192:193], v[92:93], v[188:189]
	v_pk_mul_f32 v[224:225], v[94:95], v[188:189]
	v_pk_mul_f32 v[226:227], v[96:97], v[188:189]
	v_pk_mul_f32 v[228:229], v[98:99], v[188:189]
	v_exp_f32_e32 v192, v192
	v_exp_f32_e32 v193, v193
	v_exp_f32_e32 v224, v224
	v_exp_f32_e32 v225, v225
	v_exp_f32_e32 v226, v226
	v_exp_f32_e32 v227, v227
	v_exp_f32_e32 v228, v228
	v_exp_f32_e32 v229, v229
	v_pk_add_f32 v[192:193], v[192:193], v[190:191]
	v_pk_add_f32 v[224:225], v[224:225], v[190:191]
	v_pk_add_f32 v[226:227], v[226:227], v[190:191]
	v_pk_add_f32 v[228:229], v[228:229], v[190:191]
	v_rcp_f32_e32 v92, v192
	v_rcp_f32_e32 v93, v193
	v_rcp_f32_e32 v94, v224
	v_rcp_f32_e32 v95, v225
	v_rcp_f32_e32 v96, v226
	v_rcp_f32_e32 v97, v227
	v_rcp_f32_e32 v98, v228
	v_rcp_f32_e32 v99, v229
.LBB0_623:
	v_lshl_add_u64 v[90:91], v[122:123], 0, s[0:1]
	v_pk_add_f32 v[88:89], v[88:89], v[110:111]
	v_pk_add_f32 v[86:87], v[86:87], v[112:113]
	v_pk_add_f32 v[84:85], v[84:85], v[108:109]
	s_and_b64 vcc, exec, s[8:9]
	v_pk_add_f32 v[82:83], v[82:83], v[106:107]
	v_cvt_pk_bf16_f32 v94, v94, v95
	v_cvt_pk_bf16_f32 v95, v96, v97
	v_cvt_pk_bf16_f32 v96, v98, v99
	v_cvt_pk_bf16_f32 v97, v92, v93
	global_store_dwordx4 v[90:91], v[94:97], off
	s_cbranch_vccnz .LBB0_625
	v_pk_mul_f32 v[192:193], v[82:83], v[188:189]
	v_pk_mul_f32 v[224:225], v[84:85], v[188:189]
	v_pk_mul_f32 v[226:227], v[86:87], v[188:189]
	v_pk_mul_f32 v[228:229], v[88:89], v[188:189]
	v_exp_f32_e32 v192, v192
	v_exp_f32_e32 v193, v193
	v_exp_f32_e32 v224, v224
	v_exp_f32_e32 v225, v225
	v_exp_f32_e32 v226, v226
	v_exp_f32_e32 v227, v227
	v_exp_f32_e32 v228, v228
	v_exp_f32_e32 v229, v229
	v_pk_add_f32 v[192:193], v[192:193], v[190:191]
	v_pk_add_f32 v[224:225], v[224:225], v[190:191]
	v_pk_add_f32 v[226:227], v[226:227], v[190:191]
	v_pk_add_f32 v[228:229], v[228:229], v[190:191]
	v_rcp_f32_e32 v82, v192
	v_rcp_f32_e32 v83, v193
	v_rcp_f32_e32 v84, v224
	v_rcp_f32_e32 v85, v225
	v_rcp_f32_e32 v86, v226
	v_rcp_f32_e32 v87, v227
	v_rcp_f32_e32 v88, v228
	v_rcp_f32_e32 v89, v229
.LBB0_625:
	v_cvt_pk_bf16_f32 v86, v86, v87
	v_cvt_pk_bf16_f32 v87, v88, v89
	v_cvt_pk_bf16_f32 v88, v82, v83
	v_pk_add_f32 v[80:81], v[80:81], v[118:119]
	v_pk_add_f32 v[78:79], v[78:79], v[120:121]
	v_pk_add_f32 v[76:77], v[76:77], v[116:117]
	s_and_b64 vcc, exec, s[8:9]
	v_pk_add_f32 v[82:83], v[74:75], v[114:115]
	v_cvt_pk_bf16_f32 v89, v84, v85
	global_store_dwordx4 v[90:91], v[86:89], off offset:256
	s_cbranch_vccnz .LBB0_627
	v_pk_mul_f32 v[192:193], v[76:77], v[188:189]
	v_pk_mul_f32 v[224:225], v[78:79], v[188:189]
	v_pk_mul_f32 v[226:227], v[80:81], v[188:189]
	v_pk_mul_f32 v[228:229], v[82:83], v[188:189]
	v_exp_f32_e32 v192, v192
	v_exp_f32_e32 v193, v193
	v_exp_f32_e32 v224, v224
	v_exp_f32_e32 v225, v225
	v_exp_f32_e32 v226, v226
	v_exp_f32_e32 v227, v227
	v_exp_f32_e32 v228, v228
	v_exp_f32_e32 v229, v229
	v_pk_add_f32 v[192:193], v[192:193], v[190:191]
	v_pk_add_f32 v[224:225], v[224:225], v[190:191]
	v_pk_add_f32 v[226:227], v[226:227], v[190:191]
	v_pk_add_f32 v[228:229], v[228:229], v[190:191]
	v_rcp_f32_e32 v76, v192
	v_rcp_f32_e32 v77, v193
	v_rcp_f32_e32 v78, v224
	v_rcp_f32_e32 v79, v225
	v_rcp_f32_e32 v80, v226
	v_rcp_f32_e32 v81, v227
	v_rcp_f32_e32 v82, v228
	v_rcp_f32_e32 v83, v229
; __device__ __forceinline__ float fast_sigmoid(float x) { return __builtin_amdgcn_rcpf(1.0f + __builtin_amdgcn_exp2f(-1.4426950408889634f * x)); }
; __device__ __forceinline__ u32x4 pack8(const f32x4 v0, const f32x4 v1) { u32x4 w; w.x = cvt_pk_bf16(v0[0], v0[1]); w.y = cvt_pk_bf16(v0[2], v0[3]); w.z = cvt_pk_bf16(v1[0], v1[1]); w.w = cvt_pk_bf16(v1[2], v1[3]); return w; }
;     __device__ __forceinline__ void operator()(const f32x4 (&acc)[2][2][4][2], const Unit& u, int wr, int wc, int fr_, int fq) const {
;     ...
;         for (int ai = 0; ai < 2; ++ai)
; #pragma unroll
;             for (int m = 0; m < 4; ++m)
; #pragma unroll
;                 for (int bj = 0; bj < 2; ++bj) { f32x4 v0 = acc[ai][bj][m][0], v1 = acc[ai][bj][m][1];
;                     v0 += bv[bj][0]; v1 += bv[bj][1];
;                     if (gate) {
; #pragma unroll
;                         for (int j = 0; j < 4; ++j) { v0[j] = fast_sigmoid(v0[j]); v1[j] = fast_sigmoid(v1[j]); } }
;                     *(u32x4*)(ob + (size_t)(ai * HALF + m * 16) * ld + bj * HALF) = pack8(v0, v1); }
.LBB0_627:
	v_lshl_add_u64 v[74:75], v[90:91], 0, s[0:1]
	v_pk_add_f32 v[72:73], v[72:73], v[110:111]
	v_pk_add_f32 v[70:71], v[70:71], v[112:113]
	v_pk_add_f32 v[68:69], v[68:69], v[108:109]
	s_and_b64 vcc, exec, s[8:9]
	v_pk_add_f32 v[66:67], v[66:67], v[106:107]
	v_cvt_pk_bf16_f32 v78, v78, v79
	v_cvt_pk_bf16_f32 v79, v80, v81
	v_cvt_pk_bf16_f32 v80, v82, v83
	v_cvt_pk_bf16_f32 v81, v76, v77
	global_store_dwordx4 v[74:75], v[78:81], off
	s_cbranch_vccnz .LBB0_629
	v_pk_mul_f32 v[192:193], v[66:67], v[188:189]
	v_pk_mul_f32 v[224:225], v[68:69], v[188:189]
	v_pk_mul_f32 v[226:227], v[70:71], v[188:189]
	v_pk_mul_f32 v[228:229], v[72:73], v[188:189]
	v_exp_f32_e32 v192, v192
	v_exp_f32_e32 v193, v193
	v_exp_f32_e32 v224, v224
	v_exp_f32_e32 v225, v225
	v_exp_f32_e32 v226, v226
	v_exp_f32_e32 v227, v227
	v_exp_f32_e32 v228, v228
	v_exp_f32_e32 v229, v229
	v_pk_add_f32 v[192:193], v[192:193], v[190:191]
	v_pk_add_f32 v[224:225], v[224:225], v[190:191]
	v_pk_add_f32 v[226:227], v[226:227], v[190:191]
	v_pk_add_f32 v[228:229], v[228:229], v[190:191]
	v_rcp_f32_e32 v66, v192
	v_rcp_f32_e32 v67, v193
	v_rcp_f32_e32 v68, v224
	v_rcp_f32_e32 v69, v225
	v_rcp_f32_e32 v70, v226
	v_rcp_f32_e32 v71, v227
	v_rcp_f32_e32 v72, v228
	v_rcp_f32_e32 v73, v229
.LBB0_629:
	v_cvt_pk_bf16_f32 v70, v70, v71
	v_cvt_pk_bf16_f32 v71, v72, v73
	v_cvt_pk_bf16_f32 v72, v66, v67
	v_pk_add_f32 v[64:65], v[64:65], v[118:119]
	v_pk_add_f32 v[62:63], v[62:63], v[120:121]
	v_pk_add_f32 v[60:61], v[60:61], v[116:117]
	s_and_b64 vcc, exec, s[8:9]
	v_pk_add_f32 v[66:67], v[58:59], v[114:115]
	v_cvt_pk_bf16_f32 v73, v68, v69
	global_store_dwordx4 v[74:75], v[70:73], off offset:256
	s_cbranch_vccnz .LBB0_631
	v_pk_mul_f32 v[192:193], v[60:61], v[188:189]
	v_pk_mul_f32 v[224:225], v[62:63], v[188:189]
	v_pk_mul_f32 v[226:227], v[64:65], v[188:189]
	v_pk_mul_f32 v[228:229], v[66:67], v[188:189]
	v_exp_f32_e32 v192, v192
	v_exp_f32_e32 v193, v193
	v_exp_f32_e32 v224, v224
	v_exp_f32_e32 v225, v225
	v_exp_f32_e32 v226, v226
	v_exp_f32_e32 v227, v227
	v_exp_f32_e32 v228, v228
	v_exp_f32_e32 v229, v229
	v_pk_add_f32 v[192:193], v[192:193], v[190:191]
	v_pk_add_f32 v[224:225], v[224:225], v[190:191]
	v_pk_add_f32 v[226:227], v[226:227], v[190:191]
	v_pk_add_f32 v[228:229], v[228:229], v[190:191]
	v_rcp_f32_e32 v60, v192
	v_rcp_f32_e32 v61, v193
	v_rcp_f32_e32 v62, v224
	v_rcp_f32_e32 v63, v225
	v_rcp_f32_e32 v64, v226
	v_rcp_f32_e32 v65, v227
	v_rcp_f32_e32 v66, v228
	v_rcp_f32_e32 v67, v229
.LBB0_631:
	s_mul_i32 s16, s30, 0xa0
	v_lshl_add_u64 v[58:59], v[74:75], 0, s[16:17]
	v_pk_add_f32 v[56:57], v[56:57], v[110:111]
	v_pk_add_f32 v[54:55], v[54:55], v[112:113]
	v_pk_add_f32 v[52:53], v[52:53], v[108:109]
	s_and_b64 vcc, exec, s[8:9]
	v_pk_add_f32 v[50:51], v[50:51], v[106:107]
	v_cvt_pk_bf16_f32 v62, v62, v63
	v_cvt_pk_bf16_f32 v63, v64, v65
	v_cvt_pk_bf16_f32 v64, v66, v67
	v_cvt_pk_bf16_f32 v65, v60, v61
	global_store_dwordx4 v[58:59], v[62:65], off
	s_cbranch_vccnz .LBB0_633
	v_pk_mul_f32 v[192:193], v[50:51], v[188:189]
	v_pk_mul_f32 v[224:225], v[52:53], v[188:189]
	v_pk_mul_f32 v[226:227], v[54:55], v[188:189]
	v_pk_mul_f32 v[228:229], v[56:57], v[188:189]
	v_exp_f32_e32 v192, v192
	v_exp_f32_e32 v193, v193
	v_exp_f32_e32 v224, v224
	v_exp_f32_e32 v225, v225
	v_exp_f32_e32 v226, v226
	v_exp_f32_e32 v227, v227
	v_exp_f32_e32 v228, v228
	v_exp_f32_e32 v229, v229
	v_pk_add_f32 v[192:193], v[192:193], v[190:191]
	v_pk_add_f32 v[224:225], v[224:225], v[190:191]
	v_pk_add_f32 v[226:227], v[226:227], v[190:191]
	v_pk_add_f32 v[228:229], v[228:229], v[190:191]
	v_rcp_f32_e32 v50, v192
	v_rcp_f32_e32 v51, v193
	v_rcp_f32_e32 v52, v224
	v_rcp_f32_e32 v53, v225
	v_rcp_f32_e32 v54, v226
	v_rcp_f32_e32 v55, v227
	v_rcp_f32_e32 v56, v228
	v_rcp_f32_e32 v57, v229
.LBB0_633:
	v_cvt_pk_bf16_f32 v54, v54, v55
	v_cvt_pk_bf16_f32 v55, v56, v57
	v_cvt_pk_bf16_f32 v56, v50, v51
	v_pk_add_f32 v[48:49], v[48:49], v[118:119]
	v_pk_add_f32 v[46:47], v[46:47], v[120:121]
	v_pk_add_f32 v[44:45], v[44:45], v[116:117]
	s_and_b64 vcc, exec, s[8:9]
	v_pk_add_f32 v[50:51], v[42:43], v[114:115]
	v_cvt_pk_bf16_f32 v57, v52, v53
	global_store_dwordx4 v[58:59], v[54:57], off offset:256
	s_cbranch_vccnz .LBB0_635
	v_pk_mul_f32 v[192:193], v[44:45], v[188:189]
	v_pk_mul_f32 v[224:225], v[46:47], v[188:189]
	v_pk_mul_f32 v[226:227], v[48:49], v[188:189]
	v_pk_mul_f32 v[228:229], v[50:51], v[188:189]
	v_exp_f32_e32 v192, v192
	v_exp_f32_e32 v193, v193
	v_exp_f32_e32 v224, v224
	v_exp_f32_e32 v225, v225
	v_exp_f32_e32 v226, v226
	v_exp_f32_e32 v227, v227
	v_exp_f32_e32 v228, v228
	v_exp_f32_e32 v229, v229
	v_pk_add_f32 v[192:193], v[192:193], v[190:191]
	v_pk_add_f32 v[224:225], v[224:225], v[190:191]
	v_pk_add_f32 v[226:227], v[226:227], v[190:191]
	v_pk_add_f32 v[228:229], v[228:229], v[190:191]
	v_rcp_f32_e32 v44, v192
	v_rcp_f32_e32 v45, v193
	v_rcp_f32_e32 v46, v224
	v_rcp_f32_e32 v47, v225
	v_rcp_f32_e32 v48, v226
	v_rcp_f32_e32 v49, v227
	v_rcp_f32_e32 v50, v228
	v_rcp_f32_e32 v51, v229
; __device__ __forceinline__ float fast_sigmoid(float x) { return __builtin_amdgcn_rcpf(1.0f + __builtin_amdgcn_exp2f(-1.4426950408889634f * x)); }
; __device__ __forceinline__ u32x4 pack8(const f32x4 v0, const f32x4 v1) { u32x4 w; w.x = cvt_pk_bf16(v0[0], v0[1]); w.y = cvt_pk_bf16(v0[2], v0[3]); w.z = cvt_pk_bf16(v1[0], v1[1]); w.w = cvt_pk_bf16(v1[2], v1[3]); return w; }
;     __device__ __forceinline__ void operator()(const f32x4 (&acc)[2][2][4][2], const Unit& u, int wr, int wc, int fr_, int fq) const {
;     ...
;         for (int ai = 0; ai < 2; ++ai)
; #pragma unroll
;             for (int m = 0; m < 4; ++m)
; #pragma unroll
;                 for (int bj = 0; bj < 2; ++bj) { f32x4 v0 = acc[ai][bj][m][0], v1 = acc[ai][bj][m][1];
;                     v0 += bv[bj][0]; v1 += bv[bj][1];
;                     if (gate) {
; #pragma unroll
;                         for (int j = 0; j < 4; ++j) { v0[j] = fast_sigmoid(v0[j]); v1[j] = fast_sigmoid(v1[j]); } }
;                     *(u32x4*)(ob + (size_t)(ai * HALF + m * 16) * ld + bj * HALF) = pack8(v0, v1); }
.LBB0_635:
	v_lshl_add_u64 v[42:43], v[58:59], 0, s[0:1]
	v_pk_add_f32 v[40:41], v[40:41], v[110:111]
	v_pk_add_f32 v[38:39], v[38:39], v[112:113]
	v_pk_add_f32 v[36:37], v[36:37], v[108:109]
	s_and_b64 vcc, exec, s[8:9]
	v_pk_add_f32 v[34:35], v[34:35], v[106:107]
	v_cvt_pk_bf16_f32 v46, v46, v47
	v_cvt_pk_bf16_f32 v47, v48, v49
	v_cvt_pk_bf16_f32 v48, v50, v51
	v_cvt_pk_bf16_f32 v49, v44, v45
	global_store_dwordx4 v[42:43], v[46:49], off
	s_cbranch_vccnz .LBB0_637
	v_pk_mul_f32 v[192:193], v[34:35], v[188:189]
	v_pk_mul_f32 v[224:225], v[36:37], v[188:189]
	v_pk_mul_f32 v[226:227], v[38:39], v[188:189]
	v_pk_mul_f32 v[228:229], v[40:41], v[188:189]
	v_exp_f32_e32 v192, v192
	v_exp_f32_e32 v193, v193
	v_exp_f32_e32 v224, v224
	v_exp_f32_e32 v225, v225
	v_exp_f32_e32 v226, v226
	v_exp_f32_e32 v227, v227
	v_exp_f32_e32 v228, v228
	v_exp_f32_e32 v229, v229
	v_pk_add_f32 v[192:193], v[192:193], v[190:191]
	v_pk_add_f32 v[224:225], v[224:225], v[190:191]
	v_pk_add_f32 v[226:227], v[226:227], v[190:191]
	v_pk_add_f32 v[228:229], v[228:229], v[190:191]
	v_rcp_f32_e32 v34, v192
	v_rcp_f32_e32 v35, v193
	v_rcp_f32_e32 v36, v224
	v_rcp_f32_e32 v37, v225
	v_rcp_f32_e32 v38, v226
	v_rcp_f32_e32 v39, v227
	v_rcp_f32_e32 v40, v228
	v_rcp_f32_e32 v41, v229
.LBB0_637:
	v_cvt_pk_bf16_f32 v38, v38, v39
	v_cvt_pk_bf16_f32 v39, v40, v41
	v_cvt_pk_bf16_f32 v40, v34, v35
	v_pk_add_f32 v[32:33], v[32:33], v[118:119]
	v_pk_add_f32 v[30:31], v[30:31], v[120:121]
	v_pk_add_f32 v[28:29], v[28:29], v[116:117]
	s_and_b64 vcc, exec, s[8:9]
	v_pk_add_f32 v[34:35], v[26:27], v[114:115]
	v_cvt_pk_bf16_f32 v41, v36, v37
	global_store_dwordx4 v[42:43], v[38:41], off offset:256
	s_cbranch_vccnz .LBB0_639
	v_pk_mul_f32 v[192:193], v[28:29], v[188:189]
	v_pk_mul_f32 v[224:225], v[30:31], v[188:189]
	v_pk_mul_f32 v[226:227], v[32:33], v[188:189]
	v_pk_mul_f32 v[228:229], v[34:35], v[188:189]
	v_exp_f32_e32 v192, v192
	v_exp_f32_e32 v193, v193
	v_exp_f32_e32 v224, v224
	v_exp_f32_e32 v225, v225
	v_exp_f32_e32 v226, v226
	v_exp_f32_e32 v227, v227
	v_exp_f32_e32 v228, v228
	v_exp_f32_e32 v229, v229
	v_pk_add_f32 v[192:193], v[192:193], v[190:191]
	v_pk_add_f32 v[224:225], v[224:225], v[190:191]
	v_pk_add_f32 v[226:227], v[226:227], v[190:191]
	v_pk_add_f32 v[228:229], v[228:229], v[190:191]
	v_rcp_f32_e32 v28, v192
	v_rcp_f32_e32 v29, v193
	v_rcp_f32_e32 v30, v224
	v_rcp_f32_e32 v31, v225
	v_rcp_f32_e32 v32, v226
	v_rcp_f32_e32 v33, v227
	v_rcp_f32_e32 v34, v228
	v_rcp_f32_e32 v35, v229
.LBB0_639:
	v_lshl_add_u64 v[26:27], v[42:43], 0, s[0:1]
	v_pk_add_f32 v[24:25], v[24:25], v[110:111]
	v_pk_add_f32 v[22:23], v[22:23], v[112:113]
	v_pk_add_f32 v[20:21], v[20:21], v[108:109]
	s_and_b64 vcc, exec, s[8:9]
	v_pk_add_f32 v[18:19], v[18:19], v[106:107]
	v_cvt_pk_bf16_f32 v30, v30, v31
	v_cvt_pk_bf16_f32 v31, v32, v33
	v_cvt_pk_bf16_f32 v32, v34, v35
	v_cvt_pk_bf16_f32 v33, v28, v29
	global_store_dwordx4 v[26:27], v[30:33], off
	s_cbranch_vccnz .LBB0_641
	v_pk_mul_f32 v[192:193], v[18:19], v[188:189]
	v_pk_mul_f32 v[224:225], v[20:21], v[188:189]
	v_pk_mul_f32 v[226:227], v[22:23], v[188:189]
	v_pk_mul_f32 v[228:229], v[24:25], v[188:189]
	v_exp_f32_e32 v192, v192
	v_exp_f32_e32 v193, v193
	v_exp_f32_e32 v224, v224
	v_exp_f32_e32 v225, v225
	v_exp_f32_e32 v226, v226
	v_exp_f32_e32 v227, v227
	v_exp_f32_e32 v228, v228
	v_exp_f32_e32 v229, v229
	v_pk_add_f32 v[192:193], v[192:193], v[190:191]
	v_pk_add_f32 v[224:225], v[224:225], v[190:191]
	v_pk_add_f32 v[226:227], v[226:227], v[190:191]
	v_pk_add_f32 v[228:229], v[228:229], v[190:191]
	v_rcp_f32_e32 v18, v192
	v_rcp_f32_e32 v19, v193
	v_rcp_f32_e32 v20, v224
	v_rcp_f32_e32 v21, v225
	v_rcp_f32_e32 v22, v226
	v_rcp_f32_e32 v23, v227
	v_rcp_f32_e32 v24, v228
	v_rcp_f32_e32 v25, v229
.LBB0_641:
	v_cvt_pk_bf16_f32 v22, v22, v23
	v_cvt_pk_bf16_f32 v23, v24, v25
	v_cvt_pk_bf16_f32 v24, v18, v19
	v_pk_add_f32 v[16:17], v[16:17], v[118:119]
	v_pk_add_f32 v[14:15], v[14:15], v[120:121]
	v_pk_add_f32 v[12:13], v[12:13], v[116:117]
	s_and_b64 vcc, exec, s[8:9]
	v_pk_add_f32 v[18:19], v[10:11], v[114:115]
	v_cvt_pk_bf16_f32 v25, v20, v21
	global_store_dwordx4 v[26:27], v[22:25], off offset:256
	s_cbranch_vccnz .LBB0_643
	v_pk_mul_f32 v[192:193], v[12:13], v[188:189]
	v_pk_mul_f32 v[224:225], v[14:15], v[188:189]
	v_pk_mul_f32 v[226:227], v[16:17], v[188:189]
	v_pk_mul_f32 v[228:229], v[18:19], v[188:189]
	v_exp_f32_e32 v192, v192
	v_exp_f32_e32 v193, v193
	v_exp_f32_e32 v224, v224
	v_exp_f32_e32 v225, v225
	v_exp_f32_e32 v226, v226
	v_exp_f32_e32 v227, v227
	v_exp_f32_e32 v228, v228
	v_exp_f32_e32 v229, v229
	v_pk_add_f32 v[192:193], v[192:193], v[190:191]
	v_pk_add_f32 v[224:225], v[224:225], v[190:191]
	v_pk_add_f32 v[226:227], v[226:227], v[190:191]
	v_pk_add_f32 v[228:229], v[228:229], v[190:191]
	v_rcp_f32_e32 v12, v192
	v_rcp_f32_e32 v13, v193
	v_rcp_f32_e32 v14, v224
	v_rcp_f32_e32 v15, v225
	v_rcp_f32_e32 v16, v226
	v_rcp_f32_e32 v17, v227
	v_rcp_f32_e32 v18, v228
	v_rcp_f32_e32 v19, v229
.LBB0_643:
	v_lshl_add_u64 v[10:11], v[26:27], 0, s[0:1]
	v_pk_add_f32 v[8:9], v[8:9], v[110:111]
	v_pk_add_f32 v[6:7], v[6:7], v[112:113]
	v_pk_add_f32 v[4:5], v[4:5], v[108:109]
	s_and_b64 vcc, exec, s[8:9]
	v_pk_add_f32 v[2:3], v[2:3], v[106:107]
	v_cvt_pk_bf16_f32 v14, v14, v15
	v_cvt_pk_bf16_f32 v15, v16, v17
	v_cvt_pk_bf16_f32 v16, v18, v19
	v_cvt_pk_bf16_f32 v17, v12, v13
	global_store_dwordx4 v[10:11], v[14:17], off
	s_cbranch_vccnz .LBB0_645
	v_pk_mul_f32 v[192:193], v[2:3], v[188:189]
	v_pk_mul_f32 v[224:225], v[4:5], v[188:189]
	v_pk_mul_f32 v[226:227], v[6:7], v[188:189]
	v_pk_mul_f32 v[228:229], v[8:9], v[188:189]
	v_exp_f32_e32 v192, v192
	v_exp_f32_e32 v193, v193
	v_exp_f32_e32 v224, v224
	v_exp_f32_e32 v225, v225
	v_exp_f32_e32 v226, v226
	v_exp_f32_e32 v227, v227
	v_exp_f32_e32 v228, v228
	v_exp_f32_e32 v229, v229
	v_pk_add_f32 v[192:193], v[192:193], v[190:191]
	v_pk_add_f32 v[224:225], v[224:225], v[190:191]
	v_pk_add_f32 v[226:227], v[226:227], v[190:191]
	v_pk_add_f32 v[228:229], v[228:229], v[190:191]
	v_rcp_f32_e32 v2, v192
	v_rcp_f32_e32 v3, v193
	v_rcp_f32_e32 v4, v224
	v_rcp_f32_e32 v5, v225
	v_rcp_f32_e32 v6, v226
	v_rcp_f32_e32 v7, v227
	v_rcp_f32_e32 v8, v228
	v_rcp_f32_e32 v9, v229
